# RWKV: output partials summed by the reader, processing deferred past the next chunk's first steps
# speedup vs baseline: 1.0070x; 1.0070x over previous
; __device__ __forceinline__ int otid() { int t = threadIdx.x; asm volatile("" : "+v"(t)); return t; }
; __device__ __forceinline__ void rwkv_item(const Params& p, int item, float* sm) {
;     ...
;   const int tid = otid(), lane = tid & 63, wave = tid >> 6;
;   const int sub = lane & 15, rowl = wave * 4 + (lane >> 4);
;   const int ltt = tid >> 4, lrr = tid & 15;
;   const int ch = h * 64 + lane;
;   const float kkw = p.k_k[ch], kaw = p.k_a[ch], rkw = p.r_k[ch];
;   const size_t rowb = (size_t)b * LP;
;   float S0 = 0.f, S1 = 0.f, S2 = 0.f, S3 = 0.f;
;   bf16_t pr0, pr1, pr2, pr3, pk0, pk1, pk2, pk3, pa0, pa1, pa2, pa3, pw0, pw1, pw2, pw3, pv;
;     ...
;   __syncthreads();
;   RW_LOAD(PADR)
;   RW_STORE(0, PADR)
;   __syncthreads();
.Lrw_yjoin:
	s_add_u32 s10, s10, s23
	s_addc_u32 s11, s11, 0
	v_readlane_b32 s24, v247, 9
	v_readlane_b32 s25, v247, 10
	v_readlane_b32 s26, v247, 11
	v_readlane_b32 s27, v247, 12
	s_lshl_b32 s23, s2, 8
	v_lshl_add_u32 v139, v137, 4, s23
	s_nop 1
	global_load_dwordx4 v[16:19], v139, s[24:25]
	global_load_dwordx4 v[20:23], v139, s[26:27]
	v_readlane_b32 s24, v247, 13
	v_readlane_b32 s25, v247, 14
	v_lshlrev_b32_e32 v47, 4, v137
	v_lshlrev_b32_e32 v136, 6, v138
	v_add_u32_e32 v136, 20480, v136
	v_lshlrev_b32_e32 v132, 4, v2
	v_lshl_add_u32 v133, v137, 4, v138
	v_lshlrev_b32_e32 v133, 2, v133
	v_add_u32_e32 v133, 20480, v133
	global_load_dwordx4 v[24:27], v139, s[24:25]
	v_mul_u32_u24_e32 v134, 0x510, v138
	v_mul_u32_u24_e32 v139, 0x50, v137
	v_add_u32_e32 v134, v139, v134
	v_add_u32_e32 v134, 0xb000, v134
	v_mul_u32_u24_e32 v135, 0x510, v137
	v_lshl_add_u32 v135, v138, 2, v135
	v_add_u32_e32 v135, 0xb000, v135
	v_add_u32_e32 v140, s22, v138
	s_lshl_b32 s23, s2, 7
	v_lshl_add_u32 v141, v137, 3, s23
	s_movk_i32 s19, 0x1800
	v_mad_u32_u24 v28, v140, s19, v141
	v_lshl_add_u32 v29, v140, 11, v141
	s_lshl_b32 s19, s18, 5
	s_add_i32 s19, s19, s23
	v_lshl_add_u32 v142, v137, 1, s19
	s_movk_i32 s23, 0x1800
	v_mad_u32_u24 v30, v140, s23, v142
	v_add_u32_e32 v30, 0x1000, v30
	v_add_u32_e32 v143, 0x70, v138
	v_lshl_add_u32 v31, v143, 11, v142
	s_lshl_b32 s19, s2, 4
	s_lshl_b32 s23, s18, 2
	s_add_i32 s19, s19, s23
	v_lshl_add_u32 v32, v140, 8, s19
	s_lshl_b32 s19, s2, 2
	v_lshl_add_u32 v33, v140, 6, s19
	s_mov_b32 s20, -1.0
	s_mov_b32 s21, -1.0
	s_mov_b32 s30, 1.0
	s_mov_b32 s31, 1.0
	s_mov_b32 s22, 0xbfb8aa3b
	s_mov_b32 s23, 0xbfb8aa3b
	v_mov_b32_e32 v12, 0
	v_mov_b32_e32 v13, 0
	v_mov_b32_e32 v14, 0
	v_mov_b32_e32 v15, 0
	s_barrier
	global_load_dwordx2 v[34:35], v28, s[4:5]
	global_load_dwordx2 v[36:37], v28, s[4:5] offset:2048
	global_load_dwordx2 v[38:39], v29, s[6:7]
	global_load_dwordx2 v[40:41], v29, s[8:9]
	global_load_ushort v42, v30, s[4:5]
	v_mov_b32_e32 v43, v132
	v_mov_b32_e32 v44, v133
	s_waitcnt vmcnt(0)
	v_lshlrev_b32_e32 v48, 16, v34
	v_and_b32_e32 v49, 0xffff0000, v34
	v_lshlrev_b32_e32 v50, 16, v35
	v_and_b32_e32 v51, 0xffff0000, v35
	v_lshlrev_b32_e32 v52, 16, v36
	v_and_b32_e32 v53, 0xffff0000, v36
	v_lshlrev_b32_e32 v54, 16, v37
	v_and_b32_e32 v55, 0xffff0000, v37
	v_lshlrev_b32_e32 v56, 16, v38
	v_and_b32_e32 v57, 0xffff0000, v38
	v_lshlrev_b32_e32 v58, 16, v39
	v_and_b32_e32 v59, 0xffff0000, v39
	v_lshlrev_b32_e32 v60, 16, v40
	v_and_b32_e32 v61, 0xffff0000, v40
	v_lshlrev_b32_e32 v62, 16, v41
	v_and_b32_e32 v63, 0xffff0000, v41
	v_lshlrev_b32_e32 v64, 16, v42
	v_pk_mul_f32 v[68:69], v[52:53], v[16:17]
	v_pk_mul_f32 v[70:71], v[54:55], v[18:19]
	v_pk_mul_f32 v[72:73], v[68:69], v[68:69]
	v_pk_fma_f32 v[72:73], v[70:71], v[70:71], v[72:73]
	v_pk_add_f32 v[76:77], v[56:57], s[20:21]
	v_add_f32_e32 v74, v72, v73
	v_pk_add_f32 v[78:79], v[58:59], s[20:21]
	v_pk_mul_f32 v[84:85], v[60:61], s[22:23]
	v_add_f32_dpp v74, v74, v74 quad_perm:[1,0,3,2] row_mask:0xf bank_mask:0xf bound_ctrl:1
	v_pk_mul_f32 v[86:87], v[62:63], s[22:23]
	v_pk_fma_f32 v[76:77], v[76:77], v[20:21], s[30:31]
	v_add_f32_dpp v74, v74, v74 quad_perm:[2,3,0,1] row_mask:0xf bank_mask:0xf bound_ctrl:1
	v_pk_fma_f32 v[78:79], v[78:79], v[22:23], s[30:31]
	v_exp_f32_e32 v84, v84
	v_add_f32_dpp v74, v74, v74 row_half_mirror row_mask:0xf bank_mask:0xf bound_ctrl:1
	v_exp_f32_e32 v85, v85
	v_exp_f32_e32 v86, v86
	v_add_f32_dpp v74, v74, v74 row_mirror row_mask:0xf bank_mask:0xf bound_ctrl:1
	v_exp_f32_e32 v87, v87
	v_pk_mul_f32 v[80:81], v[52:53], v[76:77]
	v_add_f32_e32 v74, 0x358637bd, v74
	v_pk_mul_f32 v[82:83], v[54:55], v[78:79]
	v_rsq_f32_e32 v120, v74
	ds_write_b128 v43, v[84:87]
	ds_write_b128 v43, v[48:51] offset:16384
	ds_write_b32 v44, v64
	ds_write_b128 v43, v[80:83] offset:4096
	v_pk_mul_f32 v[124:125], v[68:69], v[120:121] op_sel_hi:[1,0] neg_lo:[0,1] neg_hi:[0,1]
	v_pk_mul_f32 v[126:127], v[70:71], v[120:121] op_sel_hi:[1,0] neg_lo:[0,1] neg_hi:[0,1]
	v_pk_mul_f32 v[100:101], v[124:125], v[56:57] neg_lo:[1,0] neg_hi:[1,0]
	v_pk_mul_f32 v[102:103], v[126:127], v[58:59] neg_lo:[1,0] neg_hi:[1,0]
	ds_write_b128 v43, v[124:127] offset:8192
	ds_write_b128 v43, v[100:103] offset:12288
	s_cmp_lg_u32 s18, 0
	s_cbranch_scc1 .Lrw_nosb_p0
	v_pk_mul_f32 v[104:105], v[48:49], v[80:81]
	v_pk_mul_f32 v[106:107], v[50:51], v[82:83]
	v_pk_mul_f32 v[108:109], v[104:105], v[24:25]
	v_pk_fma_f32 v[108:109], v[106:107], v[26:27], v[108:109]
	v_add_f32_e32 v110, v108, v109
	s_nop 1
	v_add_f32_dpp v110, v110, v110 quad_perm:[1,0,3,2] row_mask:0xf bank_mask:0xf bound_ctrl:1
	s_nop 1
	v_add_f32_dpp v110, v110, v110 quad_perm:[2,3,0,1] row_mask:0xf bank_mask:0xf bound_ctrl:1
	s_nop 1
	v_add_f32_dpp v110, v110, v110 row_half_mirror row_mask:0xf bank_mask:0xf bound_ctrl:1
	s_nop 1
	v_add_f32_dpp v110, v110, v110 row_mirror row_mask:0xf bank_mask:0xf bound_ctrl:1
	global_store_dword v33, v110, s[16:17]

; __device__ __forceinline__ void rwkv_item(const Params& p, int item, float* sm) {
;     ...
; #pragma unroll
;       for (int t = 0; t < TC; t++) {
;         const float4 w4 = *(const float4*)(bw + 0 * TC * 64 + t * 64 + sub * 4);
;         const float4 k4 = *(const float4*)(bw + 1 * TC * 64 + t * 64 + sub * 4);
;         const float4 a4 = *(const float4*)(bw + 2 * TC * 64 + t * 64 + sub * 4);
;         const float4 b4 = *(const float4*)(bw + 3 * TC * 64 + t * 64 + sub * 4);
;         const float4 r4 = *(const float4*)(bw + 4 * TC * 64 + t * 64 + sub * 4);
;         const float v = bv[t * 16 + rowl];
;         const float sa = dpp_sum16((S0 * a4.x + S1 * a4.y) + (S2 * a4.z + S3 * a4.w));
;         S0 = (S0 * w4.x + v * k4.x) + sa * b4.x;
;         S1 = (S1 * w4.y + v * k4.y) + sa * b4.y;
;         S2 = (S2 * w4.z + v * k4.z) + sa * b4.z;
;         S3 = (S3 * w4.w + v * k4.w) + sa * b4.w;
;         yreg[t] = (S0 * r4.x + S1 * r4.y) + (S2 * r4.z + S3 * r4.w);
;       }
;     ...
;     {
;       const float* bb = sm + bi * BUF;
;       const float yv = bb[5 * TC * 64 + TC * 16 + TC + ltt * 16 + lrr];
;       const float mu = dpp_sum16(yv) * (1.f / 16.f);
;       yr[(size_t)(t0 + ltt) * D + h * 64 + rg * 16 + lrr] = f2bf(yv - mu);
;       if (lrr == 0) MU[(rowb + t0 + ltt) * 64 + h * 4 + rg] = mu;
;     }
.Lrw_noload:
	s_waitcnt lgkmcnt(5)
	v_pk_mul_f32 v[120:121], v[12:13], v[56:57]
	v_pk_fma_f32 v[120:121], v[14:15], v[58:59], v[120:121]
	v_pk_mul_f32 v[122:123], v[12:13], v[48:49]
	v_add_f32_e32 v128, v120, v121
	v_pk_mul_f32 v[124:125], v[14:15], v[50:51]
	v_pk_fma_f32 v[122:123], v[52:53], v[88:89], v[122:123] op_sel_hi:[1,0,1]
	v_add_f32_dpp v128, v128, v128 quad_perm:[1,0,3,2] row_mask:0xf bank_mask:0xf bound_ctrl:1
	v_pk_fma_f32 v[124:125], v[54:55], v[88:89], v[124:125] op_sel_hi:[1,0,1]
	ds_read_b128 v[148:151], v10 offset:4608
	v_add_f32_dpp v128, v128, v128 quad_perm:[2,3,0,1] row_mask:0xf bank_mask:0xf bound_ctrl:1
	ds_read_b128 v[156:159], v10 offset:12800
	ds_read_b128 v[138:141], v10 offset:16896
	v_add_f32_dpp v128, v128, v128 row_half_mirror row_mask:0xf bank_mask:0xf bound_ctrl:1
	ds_read_b128 v[144:147], v10 offset:512
	ds_read_b128 v[152:155], v10 offset:8704
	v_add_f32_dpp v130, v128, v128 row_mirror row_mask:0xf bank_mask:0xf bound_ctrl:1
	v_pk_fma_f32 v[12:13], v[60:61], v[130:131], v[122:123] op_sel_hi:[1,0,1]
	v_pk_fma_f32 v[14:15], v[62:63], v[130:131], v[124:125] op_sel_hi:[1,0,1]
	v_pk_mul_f32 v[126:127], v[12:13], v[80:81]
	v_pk_fma_f32 v[126:127], v[14:15], v[82:83], v[126:127]
	s_waitcnt lgkmcnt(5)
	ds_read_b128 v[56:59], v10 offset:8960
	v_pk_mul_f32 v[120:121], v[12:13], v[72:73]
	v_pk_fma_f32 v[120:121], v[14:15], v[74:75], v[120:121]
	v_pk_mul_f32 v[122:123], v[12:13], v[64:65]
	v_add_f32_e32 v128, v120, v121
	v_pk_mul_f32 v[124:125], v[14:15], v[66:67]
	v_pk_fma_f32 v[122:123], v[68:69], v[88:89], v[122:123] op_sel:[0,1,0] op_sel_hi:[1,1,1]
	v_add_f32_dpp v128, v128, v128 quad_perm:[1,0,3,2] row_mask:0xf bank_mask:0xf bound_ctrl:1
	v_pk_fma_f32 v[124:125], v[70:71], v[88:89], v[124:125] op_sel:[0,1,0] op_sel_hi:[1,1,1]
	ds_read_b128 v[52:55], v10 offset:4864
	v_add_f32_dpp v128, v128, v128 quad_perm:[2,3,0,1] row_mask:0xf bank_mask:0xf bound_ctrl:1
	ds_read_b128 v[60:63], v10 offset:13056
	ds_read_b128 v[80:83], v10 offset:17152
	v_add_f32_dpp v128, v128, v128 row_half_mirror row_mask:0xf bank_mask:0xf bound_ctrl:1
	v_add_f32_e32 v104, v126, v127
	ds_read_b128 v[48:51], v10 offset:768
	v_add_f32_dpp v130, v128, v128 row_mirror row_mask:0xf bank_mask:0xf bound_ctrl:1
	v_pk_fma_f32 v[12:13], v[76:77], v[130:131], v[122:123] op_sel_hi:[1,0,1]
	v_pk_fma_f32 v[14:15], v[78:79], v[130:131], v[124:125] op_sel_hi:[1,0,1]
	v_pk_mul_f32 v[126:127], v[12:13], v[84:85]
	v_pk_fma_f32 v[126:127], v[14:15], v[86:87], v[126:127]
	s_cmp_eq_u32 s0, 0
	s_cbranch_scc1 .Lrw_noout
	v_add_f32_e32 v166, v166, v174
	v_add_f32_e32 v167, v167, v175
	v_add_f32_e32 v168, v168, v176
	v_add_f32_e32 v169, v169, v177
	v_add_f32_e32 v170, v170, v178
	v_add_f32_e32 v171, v171, v179
	v_add_f32_e32 v172, v172, v180
	v_add_f32_e32 v173, v173, v181
	v_add_f32_e32 v166, v166, v170
	v_add_f32_e32 v167, v167, v171
	v_add_f32_e32 v168, v168, v172
	v_add_f32_e32 v169, v169, v173
	v_add_f32_e32 v166, v166, v168
	v_add_f32_e32 v167, v167, v169
	v_add_f32_e32 v120, v166, v167
	s_nop 1
	v_add_f32_dpp v122, v120, v120 quad_perm:[1,0,3,2] row_mask:0xf bank_mask:0xf bound_ctrl:1
	s_nop 1
	v_add_f32_dpp v122, v122, v122 quad_perm:[2,3,0,1] row_mask:0xf bank_mask:0xf bound_ctrl:1
	s_nop 1
	v_add_f32_dpp v122, v122, v122 row_half_mirror row_mask:0xf bank_mask:0xf bound_ctrl:1
	s_nop 1
	v_add_f32_dpp v122, v122, v122 row_mirror row_mask:0xf bank_mask:0xf bound_ctrl:1
	s_nop 0
	v_fmac_f32_e32 v120, 0xbd800000, v122
	v_mul_f32_e32 v122, 0x3d800000, v122
	v_cvt_pk_bf16_f32 v124, v120, v120
	global_store_dword v32, v122, s[14:15]
	global_store_short v31, v124, s[10:11]
	s_add_u32 s10, s10, 0x8000
	s_addc_u32 s11, s11, 0
	s_add_u32 s14, s14, 0x1000
	s_addc_u32 s15, s15, 0
.Lrw_noout:
	s_waitcnt lgkmcnt(5)
	ds_read_b128 v[72:75], v10 offset:9216
	v_pk_mul_f32 v[120:121], v[12:13], v[152:153]
	v_pk_fma_f32 v[120:121], v[14:15], v[154:155], v[120:121]
	v_pk_mul_f32 v[122:123], v[12:13], v[144:145]
	v_add_f32_e32 v128, v120, v121
	v_pk_mul_f32 v[124:125], v[14:15], v[146:147]
	v_pk_fma_f32 v[122:123], v[148:149], v[90:91], v[122:123] op_sel_hi:[1,0,1]
	v_add_f32_dpp v128, v128, v128 quad_perm:[1,0,3,2] row_mask:0xf bank_mask:0xf bound_ctrl:1
	v_pk_fma_f32 v[124:125], v[150:151], v[90:91], v[124:125] op_sel_hi:[1,0,1]
	ds_read_b128 v[68:71], v10 offset:5120
	v_add_f32_dpp v128, v128, v128 quad_perm:[2,3,0,1] row_mask:0xf bank_mask:0xf bound_ctrl:1
	ds_read_b128 v[76:79], v10 offset:13312
	ds_read_b128 v[84:87], v10 offset:17408
	v_add_f32_dpp v128, v128, v128 row_half_mirror row_mask:0xf bank_mask:0xf bound_ctrl:1
	v_add_f32_e32 v105, v126, v127
	ds_read_b128 v[64:67], v10 offset:1024
	v_add_f32_dpp v130, v128, v128 row_mirror row_mask:0xf bank_mask:0xf bound_ctrl:1
	v_pk_fma_f32 v[12:13], v[156:157], v[130:131], v[122:123] op_sel_hi:[1,0,1]
	v_pk_fma_f32 v[14:15], v[158:159], v[130:131], v[124:125] op_sel_hi:[1,0,1]
	v_pk_mul_f32 v[126:127], v[12:13], v[138:139]
	v_pk_fma_f32 v[126:127], v[14:15], v[140:141], v[126:127]
	s_waitcnt lgkmcnt(5)
; __device__ __forceinline__ void rwkv_item(const Params& p, int item, float* sm) {
;     ...
; #pragma unroll
;       for (int t = 0; t < TC; t++) {
;         const float4 w4 = *(const float4*)(bw + 0 * TC * 64 + t * 64 + sub * 4);
;         const float4 k4 = *(const float4*)(bw + 1 * TC * 64 + t * 64 + sub * 4);
;         const float4 a4 = *(const float4*)(bw + 2 * TC * 64 + t * 64 + sub * 4);
;         const float4 b4 = *(const float4*)(bw + 3 * TC * 64 + t * 64 + sub * 4);
;         const float4 r4 = *(const float4*)(bw + 4 * TC * 64 + t * 64 + sub * 4);
;         const float v = bv[t * 16 + rowl];
;         const float sa = dpp_sum16((S0 * a4.x + S1 * a4.y) + (S2 * a4.z + S3 * a4.w));
;         S0 = (S0 * w4.x + v * k4.x) + sa * b4.x;
;         S1 = (S1 * w4.y + v * k4.y) + sa * b4.y;
;         S2 = (S2 * w4.z + v * k4.z) + sa * b4.z;
;         S3 = (S3 * w4.w + v * k4.w) + sa * b4.w;
;         yreg[t] = (S0 * r4.x + S1 * r4.y) + (S2 * r4.z + S3 * r4.w);
;       }
	ds_read_b128 v[152:155], v10 offset:9472
	v_pk_mul_f32 v[120:121], v[12:13], v[56:57]
	v_pk_fma_f32 v[120:121], v[14:15], v[58:59], v[120:121]
	v_pk_mul_f32 v[122:123], v[12:13], v[48:49]
	v_add_f32_e32 v128, v120, v121
	v_pk_mul_f32 v[124:125], v[14:15], v[50:51]
	v_pk_fma_f32 v[122:123], v[52:53], v[90:91], v[122:123] op_sel:[0,1,0] op_sel_hi:[1,1,1]
	v_add_f32_dpp v128, v128, v128 quad_perm:[1,0,3,2] row_mask:0xf bank_mask:0xf bound_ctrl:1
	v_pk_fma_f32 v[124:125], v[54:55], v[90:91], v[124:125] op_sel:[0,1,0] op_sel_hi:[1,1,1]
	ds_read_b128 v[148:151], v10 offset:5376
	v_add_f32_dpp v128, v128, v128 quad_perm:[2,3,0,1] row_mask:0xf bank_mask:0xf bound_ctrl:1
	ds_read_b128 v[156:159], v10 offset:13568
	ds_read_b128 v[138:141], v10 offset:17664
	v_add_f32_dpp v128, v128, v128 row_half_mirror row_mask:0xf bank_mask:0xf bound_ctrl:1
	v_add_f32_e32 v106, v126, v127
	ds_read_b128 v[144:147], v10 offset:1280
	v_add_f32_dpp v130, v128, v128 row_mirror row_mask:0xf bank_mask:0xf bound_ctrl:1
	v_pk_fma_f32 v[12:13], v[60:61], v[130:131], v[122:123] op_sel_hi:[1,0,1]
	v_pk_fma_f32 v[14:15], v[62:63], v[130:131], v[124:125] op_sel_hi:[1,0,1]
	v_pk_mul_f32 v[126:127], v[12:13], v[80:81]
	v_pk_fma_f32 v[126:127], v[14:15], v[82:83], v[126:127]
	s_waitcnt lgkmcnt(5)
	ds_read_b128 v[56:59], v10 offset:9728
	v_pk_mul_f32 v[120:121], v[12:13], v[72:73]
	v_pk_fma_f32 v[120:121], v[14:15], v[74:75], v[120:121]
	v_pk_mul_f32 v[122:123], v[12:13], v[64:65]
	v_add_f32_e32 v128, v120, v121
	v_pk_mul_f32 v[124:125], v[14:15], v[66:67]
	v_pk_fma_f32 v[122:123], v[68:69], v[92:93], v[122:123] op_sel_hi:[1,0,1]
	v_add_f32_dpp v128, v128, v128 quad_perm:[1,0,3,2] row_mask:0xf bank_mask:0xf bound_ctrl:1
	v_pk_fma_f32 v[124:125], v[70:71], v[92:93], v[124:125] op_sel_hi:[1,0,1]
	ds_read_b128 v[52:55], v10 offset:5632
	v_add_f32_dpp v128, v128, v128 quad_perm:[2,3,0,1] row_mask:0xf bank_mask:0xf bound_ctrl:1
	ds_read_b128 v[60:63], v10 offset:13824
	ds_read_b128 v[80:83], v10 offset:17920
	v_add_f32_dpp v128, v128, v128 row_half_mirror row_mask:0xf bank_mask:0xf bound_ctrl:1
	v_add_f32_e32 v107, v126, v127
	ds_read_b128 v[48:51], v10 offset:1536
	v_add_f32_dpp v130, v128, v128 row_mirror row_mask:0xf bank_mask:0xf bound_ctrl:1
	v_pk_fma_f32 v[12:13], v[76:77], v[130:131], v[122:123] op_sel_hi:[1,0,1]
	v_pk_fma_f32 v[14:15], v[78:79], v[130:131], v[124:125] op_sel_hi:[1,0,1]
	v_pk_mul_f32 v[126:127], v[12:13], v[84:85]
	v_pk_fma_f32 v[126:127], v[14:15], v[86:87], v[126:127]
	s_waitcnt lgkmcnt(5)
	ds_read_b128 v[72:75], v10 offset:9984
	v_pk_mul_f32 v[120:121], v[12:13], v[152:153]
	v_pk_fma_f32 v[120:121], v[14:15], v[154:155], v[120:121]
	v_pk_mul_f32 v[122:123], v[12:13], v[144:145]
	v_add_f32_e32 v128, v120, v121
	v_pk_mul_f32 v[124:125], v[14:15], v[146:147]
	v_pk_fma_f32 v[122:123], v[148:149], v[92:93], v[122:123] op_sel:[0,1,0] op_sel_hi:[1,1,1]
	v_add_f32_dpp v128, v128, v128 quad_perm:[1,0,3,2] row_mask:0xf bank_mask:0xf bound_ctrl:1
	v_pk_fma_f32 v[124:125], v[150:151], v[92:93], v[124:125] op_sel:[0,1,0] op_sel_hi:[1,1,1]
	ds_read_b128 v[68:71], v10 offset:5888
	v_add_f32_dpp v128, v128, v128 quad_perm:[2,3,0,1] row_mask:0xf bank_mask:0xf bound_ctrl:1
	ds_read_b128 v[76:79], v10 offset:14080
	ds_read_b128 v[84:87], v10 offset:18176
	v_add_f32_dpp v128, v128, v128 row_half_mirror row_mask:0xf bank_mask:0xf bound_ctrl:1
	v_add_f32_e32 v108, v126, v127
	ds_read_b128 v[64:67], v10 offset:1792
	v_add_f32_dpp v130, v128, v128 row_mirror row_mask:0xf bank_mask:0xf bound_ctrl:1
	v_pk_fma_f32 v[12:13], v[156:157], v[130:131], v[122:123] op_sel_hi:[1,0,1]
	v_pk_fma_f32 v[14:15], v[158:159], v[130:131], v[124:125] op_sel_hi:[1,0,1]
	v_pk_mul_f32 v[126:127], v[12:13], v[138:139]
	v_pk_fma_f32 v[126:127], v[14:15], v[140:141], v[126:127]
	s_waitcnt lgkmcnt(5)
	ds_read_b128 v[152:155], v10 offset:10240
	v_pk_mul_f32 v[120:121], v[12:13], v[56:57]
	v_pk_fma_f32 v[120:121], v[14:15], v[58:59], v[120:121]
	v_pk_mul_f32 v[122:123], v[12:13], v[48:49]
	v_add_f32_e32 v128, v120, v121
	v_pk_mul_f32 v[124:125], v[14:15], v[50:51]
	v_pk_fma_f32 v[122:123], v[52:53], v[94:95], v[122:123] op_sel_hi:[1,0,1]
	v_add_f32_dpp v128, v128, v128 quad_perm:[1,0,3,2] row_mask:0xf bank_mask:0xf bound_ctrl:1
	v_pk_fma_f32 v[124:125], v[54:55], v[94:95], v[124:125] op_sel_hi:[1,0,1]
	ds_read_b128 v[148:151], v10 offset:6144
	v_add_f32_dpp v128, v128, v128 quad_perm:[2,3,0,1] row_mask:0xf bank_mask:0xf bound_ctrl:1
	ds_read_b128 v[156:159], v10 offset:14336
	ds_read_b128 v[138:141], v10 offset:18432
	v_add_f32_dpp v128, v128, v128 row_half_mirror row_mask:0xf bank_mask:0xf bound_ctrl:1
	v_add_f32_e32 v109, v126, v127
	ds_read_b128 v[144:147], v10 offset:2048
	v_add_f32_dpp v130, v128, v128 row_mirror row_mask:0xf bank_mask:0xf bound_ctrl:1
	v_pk_fma_f32 v[12:13], v[60:61], v[130:131], v[122:123] op_sel_hi:[1,0,1]
	v_pk_fma_f32 v[14:15], v[62:63], v[130:131], v[124:125] op_sel_hi:[1,0,1]
	v_pk_mul_f32 v[126:127], v[12:13], v[80:81]
	v_pk_fma_f32 v[126:127], v[14:15], v[82:83], v[126:127]
	s_waitcnt lgkmcnt(5)
; __device__ __forceinline__ void rwkv_item(const Params& p, int item, float* sm) {
;     ...
; #pragma unroll
;       for (int t = 0; t < TC; t++) {
;         const float4 w4 = *(const float4*)(bw + 0 * TC * 64 + t * 64 + sub * 4);
;         const float4 k4 = *(const float4*)(bw + 1 * TC * 64 + t * 64 + sub * 4);
;         const float4 a4 = *(const float4*)(bw + 2 * TC * 64 + t * 64 + sub * 4);
;         const float4 b4 = *(const float4*)(bw + 3 * TC * 64 + t * 64 + sub * 4);
;         const float4 r4 = *(const float4*)(bw + 4 * TC * 64 + t * 64 + sub * 4);
;         const float v = bv[t * 16 + rowl];
;         const float sa = dpp_sum16((S0 * a4.x + S1 * a4.y) + (S2 * a4.z + S3 * a4.w));
;         S0 = (S0 * w4.x + v * k4.x) + sa * b4.x;
;         S1 = (S1 * w4.y + v * k4.y) + sa * b4.y;
;         S2 = (S2 * w4.z + v * k4.z) + sa * b4.z;
;         S3 = (S3 * w4.w + v * k4.w) + sa * b4.w;
;         yreg[t] = (S0 * r4.x + S1 * r4.y) + (S2 * r4.z + S3 * r4.w);
;       }
	ds_read_b128 v[56:59], v10 offset:10496
	v_pk_mul_f32 v[120:121], v[12:13], v[72:73]
	v_pk_fma_f32 v[120:121], v[14:15], v[74:75], v[120:121]
	v_pk_mul_f32 v[122:123], v[12:13], v[64:65]
	v_add_f32_e32 v128, v120, v121
	v_pk_mul_f32 v[124:125], v[14:15], v[66:67]
	v_pk_fma_f32 v[122:123], v[68:69], v[94:95], v[122:123] op_sel:[0,1,0] op_sel_hi:[1,1,1]
	v_add_f32_dpp v128, v128, v128 quad_perm:[1,0,3,2] row_mask:0xf bank_mask:0xf bound_ctrl:1
	v_pk_fma_f32 v[124:125], v[70:71], v[94:95], v[124:125] op_sel:[0,1,0] op_sel_hi:[1,1,1]
	ds_read_b128 v[52:55], v10 offset:6400
	v_add_f32_dpp v128, v128, v128 quad_perm:[2,3,0,1] row_mask:0xf bank_mask:0xf bound_ctrl:1
	ds_read_b128 v[60:63], v10 offset:14592
	ds_read_b128 v[80:83], v10 offset:18688
	v_add_f32_dpp v128, v128, v128 row_half_mirror row_mask:0xf bank_mask:0xf bound_ctrl:1
	v_add_f32_e32 v110, v126, v127
	ds_read_b128 v[48:51], v10 offset:2304
	v_add_f32_dpp v130, v128, v128 row_mirror row_mask:0xf bank_mask:0xf bound_ctrl:1
	v_pk_fma_f32 v[12:13], v[76:77], v[130:131], v[122:123] op_sel_hi:[1,0,1]
	v_pk_fma_f32 v[14:15], v[78:79], v[130:131], v[124:125] op_sel_hi:[1,0,1]
	v_pk_mul_f32 v[126:127], v[12:13], v[84:85]
	v_pk_fma_f32 v[126:127], v[14:15], v[86:87], v[126:127]
	s_waitcnt lgkmcnt(5)
	ds_read_b128 v[72:75], v10 offset:10752
	v_pk_mul_f32 v[120:121], v[12:13], v[152:153]
	v_pk_fma_f32 v[120:121], v[14:15], v[154:155], v[120:121]
	v_pk_mul_f32 v[122:123], v[12:13], v[144:145]
	v_add_f32_e32 v128, v120, v121
	v_pk_mul_f32 v[124:125], v[14:15], v[146:147]
	v_pk_fma_f32 v[122:123], v[148:149], v[96:97], v[122:123] op_sel_hi:[1,0,1]
	v_add_f32_dpp v128, v128, v128 quad_perm:[1,0,3,2] row_mask:0xf bank_mask:0xf bound_ctrl:1
	v_pk_fma_f32 v[124:125], v[150:151], v[96:97], v[124:125] op_sel_hi:[1,0,1]
	ds_read_b128 v[68:71], v10 offset:6656
	v_add_f32_dpp v128, v128, v128 quad_perm:[2,3,0,1] row_mask:0xf bank_mask:0xf bound_ctrl:1
	ds_read_b128 v[76:79], v10 offset:14848
	ds_read_b128 v[84:87], v10 offset:18944
	v_add_f32_dpp v128, v128, v128 row_half_mirror row_mask:0xf bank_mask:0xf bound_ctrl:1
	v_add_f32_e32 v111, v126, v127
	ds_read_b128 v[64:67], v10 offset:2560
	v_add_f32_dpp v130, v128, v128 row_mirror row_mask:0xf bank_mask:0xf bound_ctrl:1
	v_pk_fma_f32 v[12:13], v[156:157], v[130:131], v[122:123] op_sel_hi:[1,0,1]
	v_pk_fma_f32 v[14:15], v[158:159], v[130:131], v[124:125] op_sel_hi:[1,0,1]
	v_pk_mul_f32 v[126:127], v[12:13], v[138:139]
	v_pk_fma_f32 v[126:127], v[14:15], v[140:141], v[126:127]
	s_waitcnt lgkmcnt(5)
	ds_read_b128 v[152:155], v10 offset:11008
	v_pk_mul_f32 v[120:121], v[12:13], v[56:57]
	v_pk_fma_f32 v[120:121], v[14:15], v[58:59], v[120:121]
	v_pk_mul_f32 v[122:123], v[12:13], v[48:49]
	v_add_f32_e32 v128, v120, v121
	v_pk_mul_f32 v[124:125], v[14:15], v[50:51]
	v_pk_fma_f32 v[122:123], v[52:53], v[96:97], v[122:123] op_sel:[0,1,0] op_sel_hi:[1,1,1]
	v_add_f32_dpp v128, v128, v128 quad_perm:[1,0,3,2] row_mask:0xf bank_mask:0xf bound_ctrl:1
	v_pk_fma_f32 v[124:125], v[54:55], v[96:97], v[124:125] op_sel:[0,1,0] op_sel_hi:[1,1,1]
	ds_read_b128 v[148:151], v10 offset:6912
	v_add_f32_dpp v128, v128, v128 quad_perm:[2,3,0,1] row_mask:0xf bank_mask:0xf bound_ctrl:1
	ds_read_b128 v[156:159], v10 offset:15104
	ds_read_b128 v[138:141], v10 offset:19200
	v_add_f32_dpp v128, v128, v128 row_half_mirror row_mask:0xf bank_mask:0xf bound_ctrl:1
	v_add_f32_e32 v112, v126, v127
	ds_read_b128 v[144:147], v10 offset:2816
	v_add_f32_dpp v130, v128, v128 row_mirror row_mask:0xf bank_mask:0xf bound_ctrl:1
	v_pk_fma_f32 v[12:13], v[60:61], v[130:131], v[122:123] op_sel_hi:[1,0,1]
	v_pk_fma_f32 v[14:15], v[62:63], v[130:131], v[124:125] op_sel_hi:[1,0,1]
	v_pk_mul_f32 v[126:127], v[12:13], v[80:81]
	v_pk_fma_f32 v[126:127], v[14:15], v[82:83], v[126:127]
	s_waitcnt lgkmcnt(5)
	ds_read_b128 v[56:59], v10 offset:11264
	v_pk_mul_f32 v[120:121], v[12:13], v[72:73]
	v_pk_fma_f32 v[120:121], v[14:15], v[74:75], v[120:121]
	v_pk_mul_f32 v[122:123], v[12:13], v[64:65]
	v_add_f32_e32 v128, v120, v121
	v_pk_mul_f32 v[124:125], v[14:15], v[66:67]
	v_pk_fma_f32 v[122:123], v[68:69], v[98:99], v[122:123] op_sel_hi:[1,0,1]
	v_add_f32_dpp v128, v128, v128 quad_perm:[1,0,3,2] row_mask:0xf bank_mask:0xf bound_ctrl:1
	v_pk_fma_f32 v[124:125], v[70:71], v[98:99], v[124:125] op_sel_hi:[1,0,1]
	ds_read_b128 v[52:55], v10 offset:7168
	v_add_f32_dpp v128, v128, v128 quad_perm:[2,3,0,1] row_mask:0xf bank_mask:0xf bound_ctrl:1
	ds_read_b128 v[60:63], v10 offset:15360
	ds_read_b128 v[80:83], v10 offset:19456
	v_add_f32_dpp v128, v128, v128 row_half_mirror row_mask:0xf bank_mask:0xf bound_ctrl:1
	v_add_f32_e32 v113, v126, v127
	ds_read_b128 v[48:51], v10 offset:3072
	v_add_f32_dpp v130, v128, v128 row_mirror row_mask:0xf bank_mask:0xf bound_ctrl:1
	v_pk_fma_f32 v[12:13], v[76:77], v[130:131], v[122:123] op_sel_hi:[1,0,1]
	v_pk_fma_f32 v[14:15], v[78:79], v[130:131], v[124:125] op_sel_hi:[1,0,1]
	v_pk_mul_f32 v[126:127], v[12:13], v[84:85]
	v_pk_fma_f32 v[126:127], v[14:15], v[86:87], v[126:127]
	s_waitcnt lgkmcnt(5)
; __device__ __forceinline__ void rwkv_item(const Params& p, int item, float* sm) {
;     ...
; #pragma unroll
;       for (int t = 0; t < TC; t++) {
;         const float4 w4 = *(const float4*)(bw + 0 * TC * 64 + t * 64 + sub * 4);
;         const float4 k4 = *(const float4*)(bw + 1 * TC * 64 + t * 64 + sub * 4);
;         const float4 a4 = *(const float4*)(bw + 2 * TC * 64 + t * 64 + sub * 4);
;         const float4 b4 = *(const float4*)(bw + 3 * TC * 64 + t * 64 + sub * 4);
;         const float4 r4 = *(const float4*)(bw + 4 * TC * 64 + t * 64 + sub * 4);
;         const float v = bv[t * 16 + rowl];
;         const float sa = dpp_sum16((S0 * a4.x + S1 * a4.y) + (S2 * a4.z + S3 * a4.w));
;         S0 = (S0 * w4.x + v * k4.x) + sa * b4.x;
;         S1 = (S1 * w4.y + v * k4.y) + sa * b4.y;
;         S2 = (S2 * w4.z + v * k4.z) + sa * b4.z;
;         S3 = (S3 * w4.w + v * k4.w) + sa * b4.w;
;         yreg[t] = (S0 * r4.x + S1 * r4.y) + (S2 * r4.z + S3 * r4.w);
;       }
; #pragma unroll
;       for (int t = 0; t < TC; t++) yreg[t] = dpp_sum16(yreg[t]);
;       if (sub == 0) {
; #pragma unroll
;         for (int t = 0; t < TC; t++) by[t * 16 + rowl] = yreg[t];
;       }
	ds_read_b128 v[72:75], v10 offset:11520
	v_pk_mul_f32 v[120:121], v[12:13], v[152:153]
	v_pk_fma_f32 v[120:121], v[14:15], v[154:155], v[120:121]
	v_pk_mul_f32 v[122:123], v[12:13], v[144:145]
	v_add_f32_e32 v128, v120, v121
	v_pk_mul_f32 v[124:125], v[14:15], v[146:147]
	v_pk_fma_f32 v[122:123], v[148:149], v[98:99], v[122:123] op_sel:[0,1,0] op_sel_hi:[1,1,1]
	v_add_f32_dpp v128, v128, v128 quad_perm:[1,0,3,2] row_mask:0xf bank_mask:0xf bound_ctrl:1
	v_pk_fma_f32 v[124:125], v[150:151], v[98:99], v[124:125] op_sel:[0,1,0] op_sel_hi:[1,1,1]
	ds_read_b128 v[68:71], v10 offset:7424
	v_add_f32_dpp v128, v128, v128 quad_perm:[2,3,0,1] row_mask:0xf bank_mask:0xf bound_ctrl:1
	ds_read_b128 v[76:79], v10 offset:15616
	ds_read_b128 v[84:87], v10 offset:19712
	v_add_f32_dpp v128, v128, v128 row_half_mirror row_mask:0xf bank_mask:0xf bound_ctrl:1
	v_add_f32_e32 v114, v126, v127
	ds_read_b128 v[64:67], v10 offset:3328
	v_add_f32_dpp v130, v128, v128 row_mirror row_mask:0xf bank_mask:0xf bound_ctrl:1
	v_pk_fma_f32 v[12:13], v[156:157], v[130:131], v[122:123] op_sel_hi:[1,0,1]
	v_pk_fma_f32 v[14:15], v[158:159], v[130:131], v[124:125] op_sel_hi:[1,0,1]
	v_pk_mul_f32 v[126:127], v[12:13], v[138:139]
	v_pk_fma_f32 v[126:127], v[14:15], v[140:141], v[126:127]
	s_waitcnt lgkmcnt(5)
	ds_read_b128 v[152:155], v10 offset:11776
	v_pk_mul_f32 v[120:121], v[12:13], v[56:57]
	v_pk_fma_f32 v[120:121], v[14:15], v[58:59], v[120:121]
	v_pk_mul_f32 v[122:123], v[12:13], v[48:49]
	v_add_f32_e32 v128, v120, v121
	v_pk_mul_f32 v[124:125], v[14:15], v[50:51]
	v_pk_fma_f32 v[122:123], v[52:53], v[100:101], v[122:123] op_sel_hi:[1,0,1]
	v_add_f32_dpp v128, v128, v128 quad_perm:[1,0,3,2] row_mask:0xf bank_mask:0xf bound_ctrl:1
	v_pk_fma_f32 v[124:125], v[54:55], v[100:101], v[124:125] op_sel_hi:[1,0,1]
	ds_read_b128 v[148:151], v10 offset:7680
	v_add_f32_dpp v128, v128, v128 quad_perm:[2,3,0,1] row_mask:0xf bank_mask:0xf bound_ctrl:1
	ds_read_b128 v[156:159], v10 offset:15872
	ds_read_b128 v[138:141], v10 offset:19968
	v_add_f32_dpp v128, v128, v128 row_half_mirror row_mask:0xf bank_mask:0xf bound_ctrl:1
	v_add_f32_e32 v115, v126, v127
	ds_read_b128 v[144:147], v10 offset:3584
	v_add_f32_dpp v130, v128, v128 row_mirror row_mask:0xf bank_mask:0xf bound_ctrl:1
	v_pk_fma_f32 v[12:13], v[60:61], v[130:131], v[122:123] op_sel_hi:[1,0,1]
	v_pk_fma_f32 v[14:15], v[62:63], v[130:131], v[124:125] op_sel_hi:[1,0,1]
	v_pk_mul_f32 v[126:127], v[12:13], v[80:81]
	v_pk_fma_f32 v[126:127], v[14:15], v[82:83], v[126:127]
	s_waitcnt lgkmcnt(5)
	ds_read_b128 v[56:59], v10 offset:12032
	v_pk_mul_f32 v[120:121], v[12:13], v[72:73]
	v_pk_fma_f32 v[120:121], v[14:15], v[74:75], v[120:121]
	v_pk_mul_f32 v[122:123], v[12:13], v[64:65]
	v_add_f32_e32 v128, v120, v121
	v_pk_mul_f32 v[124:125], v[14:15], v[66:67]
	v_pk_fma_f32 v[122:123], v[68:69], v[100:101], v[122:123] op_sel:[0,1,0] op_sel_hi:[1,1,1]
	v_add_f32_dpp v128, v128, v128 quad_perm:[1,0,3,2] row_mask:0xf bank_mask:0xf bound_ctrl:1
	v_pk_fma_f32 v[124:125], v[70:71], v[100:101], v[124:125] op_sel:[0,1,0] op_sel_hi:[1,1,1]
	ds_read_b128 v[52:55], v10 offset:7936
	v_add_f32_dpp v128, v128, v128 quad_perm:[2,3,0,1] row_mask:0xf bank_mask:0xf bound_ctrl:1
	ds_read_b128 v[60:63], v10 offset:16128
	ds_read_b128 v[80:83], v10 offset:20224
	v_add_f32_dpp v128, v128, v128 row_half_mirror row_mask:0xf bank_mask:0xf bound_ctrl:1
	v_add_f32_e32 v116, v126, v127
	ds_read_b128 v[48:51], v10 offset:3840
	v_add_f32_dpp v130, v128, v128 row_mirror row_mask:0xf bank_mask:0xf bound_ctrl:1
	v_pk_fma_f32 v[12:13], v[76:77], v[130:131], v[122:123] op_sel_hi:[1,0,1]
	v_pk_fma_f32 v[14:15], v[78:79], v[130:131], v[124:125] op_sel_hi:[1,0,1]
	v_pk_mul_f32 v[126:127], v[12:13], v[84:85]
	v_pk_fma_f32 v[126:127], v[14:15], v[86:87], v[126:127]
	s_waitcnt lgkmcnt(5)
	v_pk_mul_f32 v[120:121], v[12:13], v[152:153]
	v_pk_fma_f32 v[120:121], v[14:15], v[154:155], v[120:121]
	v_pk_mul_f32 v[122:123], v[12:13], v[144:145]
	v_add_f32_e32 v128, v120, v121
	v_pk_mul_f32 v[124:125], v[14:15], v[146:147]
	v_pk_fma_f32 v[122:123], v[148:149], v[102:103], v[122:123] op_sel_hi:[1,0,1]
	v_add_f32_dpp v128, v128, v128 quad_perm:[1,0,3,2] row_mask:0xf bank_mask:0xf bound_ctrl:1
	v_pk_fma_f32 v[124:125], v[150:151], v[102:103], v[124:125] op_sel_hi:[1,0,1]
	s_nop 0
	v_add_f32_dpp v128, v128, v128 quad_perm:[2,3,0,1] row_mask:0xf bank_mask:0xf bound_ctrl:1
	s_nop 1
	v_add_f32_dpp v128, v128, v128 row_half_mirror row_mask:0xf bank_mask:0xf bound_ctrl:1
	v_add_f32_e32 v117, v126, v127
	s_nop 0
	v_add_f32_dpp v130, v128, v128 row_mirror row_mask:0xf bank_mask:0xf bound_ctrl:1
	v_pk_fma_f32 v[12:13], v[156:157], v[130:131], v[122:123] op_sel_hi:[1,0,1]
	v_pk_fma_f32 v[14:15], v[158:159], v[130:131], v[124:125] op_sel_hi:[1,0,1]
	v_pk_mul_f32 v[126:127], v[12:13], v[138:139]
	v_pk_fma_f32 v[126:127], v[14:15], v[140:141], v[126:127]
	s_waitcnt lgkmcnt(0)
	v_pk_mul_f32 v[120:121], v[12:13], v[56:57]
	v_pk_fma_f32 v[120:121], v[14:15], v[58:59], v[120:121]
	v_pk_mul_f32 v[122:123], v[12:13], v[48:49]
	v_add_f32_e32 v128, v120, v121
	v_pk_mul_f32 v[124:125], v[14:15], v[50:51]
	v_pk_fma_f32 v[122:123], v[52:53], v[102:103], v[122:123] op_sel:[0,1,0] op_sel_hi:[1,1,1]
	v_add_f32_dpp v128, v128, v128 quad_perm:[1,0,3,2] row_mask:0xf bank_mask:0xf bound_ctrl:1
	v_pk_fma_f32 v[124:125], v[54:55], v[102:103], v[124:125] op_sel:[0,1,0] op_sel_hi:[1,1,1]
	s_nop 0
	v_add_f32_dpp v128, v128, v128 quad_perm:[2,3,0,1] row_mask:0xf bank_mask:0xf bound_ctrl:1
	s_nop 1
	v_add_f32_dpp v128, v128, v128 row_half_mirror row_mask:0xf bank_mask:0xf bound_ctrl:1
	v_add_f32_e32 v118, v126, v127
	s_nop 0
	v_add_f32_dpp v130, v128, v128 row_mirror row_mask:0xf bank_mask:0xf bound_ctrl:1
	v_pk_fma_f32 v[12:13], v[60:61], v[130:131], v[122:123] op_sel_hi:[1,0,1]
	v_pk_fma_f32 v[14:15], v[62:63], v[130:131], v[124:125] op_sel_hi:[1,0,1]
	v_pk_mul_f32 v[126:127], v[12:13], v[80:81]
	v_pk_fma_f32 v[126:127], v[14:15], v[82:83], v[126:127]
	v_add_f32_e32 v119, v126, v127
	s_xor_b32 s29, s1, 0x5800
	v_add_u32_e32 v43, s29, v132
	v_add_u32_e32 v44, s29, v133
	ds_write_b128 v134, v[104:107]
	ds_write_b128 v134, v[108:111] offset:16
	ds_write_b128 v134, v[112:115] offset:32
	ds_write_b128 v134, v[116:119] offset:48
	s_cmp_eq_u32 s0, 512
	s_cbranch_scc1 .Lrw_noprep
	s_waitcnt vmcnt(0)
	v_lshlrev_b32_e32 v48, 16, v34
	v_and_b32_e32 v49, 0xffff0000, v34
	v_lshlrev_b32_e32 v50, 16, v35
	v_and_b32_e32 v51, 0xffff0000, v35
	v_lshlrev_b32_e32 v52, 16, v36
	v_and_b32_e32 v53, 0xffff0000, v36
	v_lshlrev_b32_e32 v54, 16, v37
	v_and_b32_e32 v55, 0xffff0000, v37
	v_lshlrev_b32_e32 v56, 16, v38
	v_and_b32_e32 v57, 0xffff0000, v38
	v_lshlrev_b32_e32 v58, 16, v39
	v_and_b32_e32 v59, 0xffff0000, v39
	v_lshlrev_b32_e32 v60, 16, v40
	v_and_b32_e32 v61, 0xffff0000, v40
	v_lshlrev_b32_e32 v62, 16, v41
	v_and_b32_e32 v63, 0xffff0000, v41
	v_lshlrev_b32_e32 v64, 16, v42
	v_pk_mul_f32 v[68:69], v[52:53], v[16:17]
	v_pk_mul_f32 v[70:71], v[54:55], v[18:19]
	v_pk_mul_f32 v[72:73], v[68:69], v[68:69]
	v_pk_fma_f32 v[72:73], v[70:71], v[70:71], v[72:73]
	v_pk_add_f32 v[76:77], v[56:57], s[20:21]
	v_add_f32_e32 v74, v72, v73
	v_pk_add_f32 v[78:79], v[58:59], s[20:21]
	v_pk_mul_f32 v[84:85], v[60:61], s[22:23]
	v_add_f32_dpp v74, v74, v74 quad_perm:[1,0,3,2] row_mask:0xf bank_mask:0xf bound_ctrl:1
	v_pk_mul_f32 v[86:87], v[62:63], s[22:23]
	v_pk_fma_f32 v[76:77], v[76:77], v[20:21], s[30:31]
	v_add_f32_dpp v74, v74, v74 quad_perm:[2,3,0,1] row_mask:0xf bank_mask:0xf bound_ctrl:1
	v_pk_fma_f32 v[78:79], v[78:79], v[22:23], s[30:31]
	v_exp_f32_e32 v84, v84
	v_add_f32_dpp v74, v74, v74 row_half_mirror row_mask:0xf bank_mask:0xf bound_ctrl:1
	v_exp_f32_e32 v85, v85
	v_exp_f32_e32 v86, v86
	v_add_f32_dpp v74, v74, v74 row_mirror row_mask:0xf bank_mask:0xf bound_ctrl:1
	v_exp_f32_e32 v87, v87
	v_pk_mul_f32 v[80:81], v[52:53], v[76:77]
	v_add_f32_e32 v74, 0x358637bd, v74
	v_pk_mul_f32 v[82:83], v[54:55], v[78:79]
	v_rsq_f32_e32 v120, v74
	ds_write_b128 v43, v[84:87]
	ds_write_b128 v43, v[48:51] offset:16384
	ds_write_b32 v44, v64
	ds_write_b128 v43, v[80:83] offset:4096
	v_pk_mul_f32 v[124:125], v[68:69], v[120:121] op_sel_hi:[1,0] neg_lo:[0,1] neg_hi:[0,1]
	v_pk_mul_f32 v[126:127], v[70:71], v[120:121] op_sel_hi:[1,0] neg_lo:[0,1] neg_hi:[0,1]
	v_pk_mul_f32 v[100:101], v[124:125], v[56:57] neg_lo:[1,0] neg_hi:[1,0]
	v_pk_mul_f32 v[102:103], v[126:127], v[58:59] neg_lo:[1,0] neg_hi:[1,0]
	ds_write_b128 v43, v[124:127] offset:8192
	ds_write_b128 v43, v[100:103] offset:12288
	s_cmp_lg_u32 s18, 0
	s_cbranch_scc1 .Lrw_nosb_p1
	v_pk_mul_f32 v[104:105], v[48:49], v[80:81]
	v_pk_mul_f32 v[106:107], v[50:51], v[82:83]
	v_pk_mul_f32 v[108:109], v[104:105], v[24:25]
	v_pk_fma_f32 v[108:109], v[106:107], v[26:27], v[108:109]
	v_add_f32_e32 v110, v108, v109
	s_nop 1
	v_add_f32_dpp v110, v110, v110 quad_perm:[1,0,3,2] row_mask:0xf bank_mask:0xf bound_ctrl:1
	s_nop 1
	v_add_f32_dpp v110, v110, v110 quad_perm:[2,3,0,1] row_mask:0xf bank_mask:0xf bound_ctrl:1
	s_nop 1
	v_add_f32_dpp v110, v110, v110 row_half_mirror row_mask:0xf bank_mask:0xf bound_ctrl:1
	s_nop 1
	v_add_f32_dpp v110, v110, v110 row_mirror row_mask:0xf bank_mask:0xf bound_ctrl:1
	global_store_dword v33, v110, s[16:17]

; __device__ __forceinline__ void rwkv_item(const Params& p, int item, float* sm) {
;     ...
;   for (int c = 0; c < NCH; c++) {
;     const int bi = c & 1;
;     const int t0 = PADR + c * TC;
;     if (c + 1 < NCH) RW_LOAD(t0 + TC)
;     ...
;     __syncthreads();
;     {
;       const float* bb = sm + bi * BUF;
;       const float yv = bb[5 * TC * 64 + TC * 16 + TC + ltt * 16 + lrr];
;       const float mu = dpp_sum16(yv) * (1.f / 16.f);
;       yr[(size_t)(t0 + ltt) * D + h * 64 + rg * 16 + lrr] = f2bf(yv - mu);
;       if (lrr == 0) MU[(rowb + t0 + ltt) * 64 + h * 4 + rg] = mu;
;     }
;   }
.Lrw_noprep:
	v_add_u32_e32 v10, s29, v47
	v_add_u32_e32 v11, s29, v136
	s_waitcnt lgkmcnt(0)
	s_barrier
	ds_read_b32 v166, v135
	ds_read_b32 v167, v135 offset:80
	ds_read_b32 v168, v135 offset:160
	ds_read_b32 v169, v135 offset:240
	ds_read_b32 v170, v135 offset:320
	ds_read_b32 v171, v135 offset:400
	ds_read_b32 v172, v135 offset:480
	ds_read_b32 v173, v135 offset:560
	ds_read_b32 v174, v135 offset:640
	ds_read_b32 v175, v135 offset:720
	ds_read_b32 v176, v135 offset:800
	ds_read_b32 v177, v135 offset:880
	ds_read_b32 v178, v135 offset:960
	ds_read_b32 v179, v135 offset:1040
	ds_read_b32 v180, v135 offset:1120
	ds_read_b32 v181, v135 offset:1200
	ds_read_b128 v[56:59], v10 offset:8192
	ds_read_b128 v[48:51], v10
	ds_read_b128 v[52:55], v10 offset:4096
	ds_read_b128 v[60:63], v10 offset:12288
	ds_read_b128 v[80:83], v10 offset:16384
	ds_read_b128 v[88:91], v11 offset:0
	ds_read_b128 v[92:95], v11 offset:16
	ds_read_b128 v[96:99], v11 offset:32
	ds_read_b128 v[100:103], v11 offset:48
	ds_read_b128 v[72:75], v10 offset:8448
	ds_read_b128 v[64:67], v10 offset:256
	ds_read_b128 v[68:71], v10 offset:4352
	ds_read_b128 v[76:79], v10 offset:12544
	ds_read_b128 v[84:87], v10 offset:16640
	s_mov_b32 s1, s29
	s_add_i32 s0, s0, 1
	s_cmp_lg_u32 s0, 513
	s_cbranch_scc1 .Lrw_chunk
	s_waitcnt lgkmcnt(0)
	v_add_f32_e32 v166, v166, v174
	v_add_f32_e32 v167, v167, v175
	v_add_f32_e32 v168, v168, v176
	v_add_f32_e32 v169, v169, v177
	v_add_f32_e32 v170, v170, v178
	v_add_f32_e32 v171, v171, v179
	v_add_f32_e32 v172, v172, v180
	v_add_f32_e32 v173, v173, v181
	v_add_f32_e32 v166, v166, v170
	v_add_f32_e32 v167, v167, v171
	v_add_f32_e32 v168, v168, v172
	v_add_f32_e32 v169, v169, v173
	v_add_f32_e32 v166, v166, v168
	v_add_f32_e32 v167, v167, v169
	v_add_f32_e32 v120, v166, v167
	s_nop 1
	v_add_f32_dpp v122, v120, v120 quad_perm:[1,0,3,2] row_mask:0xf bank_mask:0xf bound_ctrl:1
	s_nop 1
	v_add_f32_dpp v122, v122, v122 quad_perm:[2,3,0,1] row_mask:0xf bank_mask:0xf bound_ctrl:1
	s_nop 1
	v_add_f32_dpp v122, v122, v122 row_half_mirror row_mask:0xf bank_mask:0xf bound_ctrl:1
	s_nop 1
	v_add_f32_dpp v122, v122, v122 row_mirror row_mask:0xf bank_mask:0xf bound_ctrl:1
	s_nop 0
	v_fmac_f32_e32 v120, 0xbd800000, v122
	v_mul_f32_e32 v122, 0x3d800000, v122
	v_cvt_pk_bf16_f32 v124, v120, v120
	global_store_dword v32, v122, s[14:15]
	global_store_short v31, v124, s[10:11]
	s_add_u32 s10, s10, 0x8000
	s_addc_u32 s11, s11, 0
	s_add_u32 s14, s14, 0x1000
	s_addc_u32 s15, s15, 0
	s_branch .LBB0_504
